# sample-attn LDS-DMA of step i+2 issued after K pass 1 instead of right after the barrier
# speedup vs baseline: 1.0135x; 1.0032x over previous
.LBB0_1862:
	s_or_b64 exec, exec, s[48:49]
	s_waitcnt lgkmcnt(0)
	s_barrier
	s_cmp_lg_u32 s78, s79
	s_cbranch_scc0 .LBB0_1879

.LBB0_1867:
	v_add_u32_e32 v204, 0, v216
	v_add_u32_e32 v154, 0x12080, v204
	v_add_u32_e32 v196, 0x120c0, v204
	ds_read_b128 v[154:157], v154
	ds_read_b128 v[196:199], v196
	v_and_or_b32 v200, s50, 48, v183
	v_mad_u32_u24 v205, v200, s77, v185
	v_add_u32_e32 v237, 0x12100, v204
	v_mfma_f32_16x16x32_bf16 v[200:203], v[2:5], v[146:149], 0
	ds_read_b128 v[238:241], v237
	v_mfma_f32_16x16x32_bf16 v[220:223], v[6:9], v[146:149], 0
	v_mfma_f32_16x16x32_bf16 v[224:227], v[10:13], v[146:149], 0
	v_mfma_f32_16x16x32_bf16 v[146:149], v[14:17], v[146:149], 0
	v_mfma_f32_16x16x32_bf16 v[200:203], v[18:21], v[150:153], v[200:203]
	v_mfma_f32_16x16x32_bf16 v[220:223], v[22:25], v[150:153], v[220:223]
	v_mfma_f32_16x16x32_bf16 v[224:227], v[26:29], v[150:153], v[224:227]
	v_mfma_f32_16x16x32_bf16 v[146:149], v[30:33], v[150:153], v[146:149]
	v_add_u32_e32 v150, 0x12140, v204
	ds_read_b128 v[150:153], v150
	s_waitcnt lgkmcnt(2)
	v_mfma_f32_16x16x32_bf16 v[200:203], v[34:37], v[154:157], v[200:203]
	v_mfma_f32_16x16x32_bf16 v[220:223], v[38:41], v[154:157], v[220:223]
	v_mfma_f32_16x16x32_bf16 v[224:227], v[42:45], v[154:157], v[224:227]
	v_mfma_f32_16x16x32_bf16 v[146:149], v[46:49], v[154:157], v[146:149]
	v_add_u32_e32 v154, 0x12180, v204
	ds_read_b128 v[154:157], v154
	v_mfma_f32_16x16x32_bf16 v[200:203], v[50:53], v[196:199], v[200:203]
	v_mfma_f32_16x16x32_bf16 v[220:223], v[54:57], v[196:199], v[220:223]
	v_mfma_f32_16x16x32_bf16 v[224:227], v[58:61], v[196:199], v[224:227]
	v_mfma_f32_16x16x32_bf16 v[146:149], v[62:65], v[196:199], v[146:149]
	v_add_u32_e32 v196, 0x121c0, v204
	ds_read_b128 v[196:199], v196
	s_waitcnt lgkmcnt(3)
	v_mfma_f32_16x16x32_bf16 v[200:203], v[66:69], v[238:241], v[200:203]
	v_mfma_f32_16x16x32_bf16 v[220:223], v[70:73], v[238:241], v[220:223]
	v_mfma_f32_16x16x32_bf16 v[224:227], v[74:77], v[238:241], v[224:227]
	v_mfma_f32_16x16x32_bf16 v[238:241], v[78:81], v[238:241], v[146:149]
	s_nop 2
	ds_read_b128 v[146:149], v205
	s_waitcnt lgkmcnt(3)
	v_mfma_f32_16x16x32_bf16 v[200:203], v[82:85], v[150:153], v[200:203]
	v_mfma_f32_16x16x32_bf16 v[220:223], v[86:89], v[150:153], v[220:223]
	v_mfma_f32_16x16x32_bf16 v[224:227], v[90:93], v[150:153], v[224:227]
	v_mfma_f32_16x16x32_bf16 v[238:241], v[94:97], v[150:153], v[238:241]
	ds_read_b128 v[150:153], v205 offset:64
	s_waitcnt lgkmcnt(3)
	v_mfma_f32_16x16x32_bf16 v[200:203], v[98:101], v[154:157], v[200:203]
	v_mfma_f32_16x16x32_bf16 v[220:223], v[102:105], v[154:157], v[220:223]
	v_mfma_f32_16x16x32_bf16 v[224:227], v[106:109], v[154:157], v[224:227]
	v_mfma_f32_16x16x32_bf16 v[154:157], v[110:113], v[154:157], v[238:241]
	s_waitcnt lgkmcnt(2)
	v_mfma_f32_16x16x32_bf16 v[220:223], v[118:121], v[196:199], v[220:223]
	v_mfma_f32_16x16x32_bf16 v[154:157], v[126:129], v[196:199], v[154:157]
	v_mfma_f32_16x16x32_bf16 v[200:203], v[114:117], v[196:199], v[200:203]
	v_mfma_f32_16x16x32_bf16 v[224:227], v[122:125], v[196:199], v[224:227]
	ds_read_b128 v[196:199], v217
	ds_read_b128 v[242:245], v214 offset:128
	ds_read_b32 v255, v218
	s_nop 4
	v_mul_f32_e32 v204, v201, v201
	v_mul_f32_e32 v205, v203, v203
	v_fmac_f32_e32 v204, v200, v200
	v_fmac_f32_e32 v205, v202, v202
	v_add_f32_e32 v204, v204, v205
	v_mul_f32_e32 v205, v221, v221
	v_mul_f32_e32 v237, v223, v223
	v_fmac_f32_e32 v205, v220, v220
	v_fmac_f32_e32 v237, v222, v222
	v_add_f32_e32 v205, v205, v237
	v_add_f32_e32 v204, v204, v205
	v_mul_f32_e32 v205, v225, v225
	v_mul_f32_e32 v237, v227, v227
	v_fmac_f32_e32 v205, v224, v224
	v_fmac_f32_e32 v237, v226, v226
	v_add_f32_e32 v205, v205, v237
	v_add_f32_e32 v204, v204, v205
	v_mul_f32_e32 v205, v155, v155
	v_mul_f32_e32 v237, v157, v157
	v_fmac_f32_e32 v205, v154, v154
	v_fmac_f32_e32 v237, v156, v156
	v_add_f32_e32 v205, v205, v237
	v_add_f32_e32 v204, v204, v205
	v_mov_b32_e32 v205, v204
	v_cvt_pk_bf16_f32 v200, v200, v201
	v_cvt_pk_bf16_f32 v201, v202, v203
	v_permlane16_swap_b32_e32 v204, v205
	v_cvt_pk_bf16_f32 v202, v220, v221
	v_cvt_pk_bf16_f32 v203, v222, v223
	v_add_f32_e32 v204, v204, v205
	v_mov_b32_e32 v205, v204
	v_cvt_pk_bf16_f32 v220, v224, v225
	v_cvt_pk_bf16_f32 v221, v226, v227
	v_permlane32_swap_b32_e32 v204, v205
	v_cvt_pk_bf16_f32 v222, v154, v155
	v_cvt_pk_bf16_f32 v223, v156, v157
	v_add_f32_e32 v204, v204, v205
	s_waitcnt lgkmcnt(0)
	v_cndmask_b32_e64 v242, 0, v242, s[4:5]
	v_cndmask_b32_e64 v243, 0, v243, s[4:5]
	v_mfma_f32_16x16x32_bf16 v[238:241], v[174:177], v[200:203], 0
	v_cndmask_b32_e64 v244, 0, v244, s[4:5]
	v_cndmask_b32_e64 v245, 0, v245, s[4:5]
	v_mfma_f32_16x16x32_bf16 v[238:241], v[246:249], v[220:223], v[238:241]
	v_add_f32_e32 v255, v204, v255
	v_fmamk_f32 v255, v255, 0x3c2aaaab, v231
	v_mfma_f32_16x16x32_bf16 v[238:241], v[242:245], v[196:199], v[238:241]
	v_rsq_f32_e32 v255, v255
	s_add_i32 s50, s50, 16
	v_add_u32_e32 v218, 64, v218
	v_add_u32_e32 v217, 0x500, v217
	v_add_u32_e32 v216, 0x2100, v216
	v_mov_b32_e32 v178, v179
	v_mov_b32_e32 v179, v180
	v_mov_b32_e32 v180, v219
	v_mul_f32_e32 v200, v238, v255
	v_mul_f32_e32 v201, v239, v255
	v_mul_f32_e32 v202, v240, v255
	v_mul_f32_e32 v203, v241, v255
	s_nop 0
	v_permlane16_swap_b32_e32 v200, v201
	s_nop 0
	v_permlane16_swap_b32_e32 v202, v203
	s_nop 1
	v_permlane32_swap_b32_e32 v200, v202
	v_mov_b32_e32 v219, v200
	s_cmpk_lg_i32 s50, 48
	s_cbranch_scc1 .Lsa_nodma
	s_ashr_i32 s89, s46, 31
	s_mov_b32 s88, s46
	s_lshl_b64 s[88:89], s[88:89], 7
	s_lshl_b32 s90, s80, 6
	s_and_b32 s90, s90, 64
	s_or_b32 s88, s88, s90
	s_lshl_b64 s[90:91], s[88:89], 10
	s_lshl_b64 s[88:89], s[88:89], 7
	v_lshl_add_u64 v[204:205], v[158:159], 0, s[90:91]
	v_lshl_add_u64 v[200:201], v[204:205], 0, s[20:21]
	s_mov_b32 m0, s54
	s_nop 0
	global_load_lds_dwordx4 v[200:201], off
	v_lshl_add_u64 v[200:201], v[204:205], 0, s[30:31]
	s_mov_b32 m0, s55
	s_nop 0
	global_load_lds_dwordx4 v[200:201], off
	v_lshl_add_u64 v[200:201], v[204:205], 0, s[34:35]
	s_mov_b32 m0, s56
	s_nop 0
	global_load_lds_dwordx4 v[200:201], off
	v_lshl_add_u64 v[200:201], v[204:205], 0, s[36:37]
	s_mov_b32 m0, s57
	s_nop 0
	global_load_lds_dwordx4 v[200:201], off
	v_lshl_add_u64 v[200:201], v[204:205], 0, s[38:39]
	s_mov_b32 m0, s58
	s_nop 0
	global_load_lds_dwordx4 v[200:201], off
	v_lshl_add_u64 v[200:201], v[204:205], 0, s[40:41]
	s_mov_b32 m0, s59
	s_nop 0
	global_load_lds_dwordx4 v[200:201], off
	v_lshl_add_u64 v[200:201], v[204:205], 0, s[42:43]
	s_mov_b32 m0, s60
	s_nop 0
	global_load_lds_dwordx4 v[200:201], off
	v_lshl_add_u64 v[200:201], v[204:205], 0, s[44:45]
	s_mov_b32 m0, s61
	s_nop 0
	global_load_lds_dwordx4 v[200:201], off
	v_lshl_add_u64 v[200:201], v[160:161], 0, s[88:89]
	s_mov_b32 m0, s28
	s_nop 0
	global_load_lds_dwordx4 v[200:201], off
.Lsa_nodma:
	s_cmpk_eq_i32 s50, 0x50
	s_cbranch_scc0 .LBB0_1867
